# SwiGLU GEMM: next unit's first A stage issued ahead of the epilogue stores; peeled entry relaxes three counted waits
# speedup vs baseline: 1.0019x; 1.0019x over previous
; #define PG8_STAGE(bufoff, gbase, voff) do { _Pragma("unroll") for (int _i = 0; _i < 2; ++_i) \
;         __builtin_amdgcn_global_load_lds((const unsigned*)((const char*)(gbase) + (voff)[_i]), (PG8_LAS unsigned*)(lds + (bufoff) + ldsw + _i * 8192), 16, 0, 0); } while (0)
; #define PG8_LDA(dst, b, h) do { _Pragma("unroll") for (int m = 0; m < 4; ++m) _Pragma("unroll") for (int k = 0; k < 2; ++k) dst[m][k] = *(const PG8_LAS bf16x8*)(lds + PG8_SA(b, h) + aoff + m * 2048 + k * 1024); } while (0)
; #define PG8_LDB(dst, b, h) do { _Pragma("unroll") for (int n = 0; n < 2; ++n) _Pragma("unroll") for (int k = 0; k < 2; ++k) dst[n][k] = *(const PG8_LAS bf16x8*)(lds + PG8_SB(b, h) + boff + n * 2048 + k * 1024); } while (0)
; #define PG8_WAIT_V(n) asm volatile("s_waitcnt vmcnt(" #n ")" ::: "memory")
; #define PG8_WAIT_L(n) asm volatile("s_waitcnt lgkmcnt(" #n ")" ::: "memory")
; #define PG8_BAR __builtin_amdgcn_s_barrier()
; #define PG8_SCHED __builtin_amdgcn_sched_barrier(0)
; template <class Epi, class Sched, bool ALIGN_EPI = false, bool SP2 = false>
; __device__ __forceinline__ void gemm_phase(PG8_LAS unsigned char* lds, const Gemm g, const Sched& S, const Epi& E, const int tid_in) {
;     ...
;             PG8_LDB(B0, 0, 0); PG8_LDB(B1, 0, 1); PG8_SCHED; PG8_LDA(At, 0, 0); PG8_STAGE(PG8_SA(1, 1), a1 + hstep, voffA);
;             PG8_WAIT_V(8); PG8_WAIT_L(0); PG8_BAR; PG8_MMA(0, 0, At, B0); PG8_MMA(0, 1, At, B1); PG8_BAR; PG8_SCHED;
;     ...
; #pragma unroll
;         for (int a = 0; a < 2; ++a)
; #pragma unroll
;             for (int b = 0; b < 2; ++b)
; #pragma unroll
;                 for (int m = 0; m < 4; ++m)
; #pragma unroll
;                     for (int n = 0; n < 2; ++n) acc[a][b][m][n] = (f32x4){0.f, 0.f, 0.f, 0.f};
.LBB0_103:
	s_add_i32 s59, s16, -2
	s_add_u32 s28, s28, 0x40080
	s_addc_u32 s29, s29, 0
	s_add_u32 s60, s34, 0x100
	v_mov_b32_e32 v2, 0
	s_addc_u32 s61, s35, 0
	s_mov_b32 s34, 0
	v_mov_b32_e32 v3, v2
	v_mov_b32_e32 v4, v2
	v_mov_b32_e32 v5, v2
	v_mov_b32_e32 v10, v2
	v_mov_b32_e32 v11, v2
	v_mov_b32_e32 v12, v2
	v_mov_b32_e32 v13, v2
	v_mov_b32_e32 v18, v2
	v_mov_b32_e32 v19, v2
	v_mov_b32_e32 v20, v2
	v_mov_b32_e32 v21, v2
	v_mov_b32_e32 v26, v2
	v_mov_b32_e32 v27, v2
	v_mov_b32_e32 v28, v2
	v_mov_b32_e32 v29, v2
	v_mov_b32_e32 v34, v2
	v_mov_b32_e32 v35, v2
	v_mov_b32_e32 v36, v2
	v_mov_b32_e32 v37, v2
	v_mov_b32_e32 v42, v2
	v_mov_b32_e32 v43, v2
	v_mov_b32_e32 v44, v2
	v_mov_b32_e32 v45, v2
	v_mov_b32_e32 v50, v2
	v_mov_b32_e32 v51, v2
	v_mov_b32_e32 v52, v2
	v_mov_b32_e32 v53, v2
	v_mov_b32_e32 v58, v2
	v_mov_b32_e32 v59, v2
	v_mov_b32_e32 v60, v2
	v_mov_b32_e32 v61, v2
	v_mov_b32_e32 v6, v2
	v_mov_b32_e32 v7, v2
	v_mov_b32_e32 v8, v2
	v_mov_b32_e32 v9, v2
	v_mov_b32_e32 v14, v2
	v_mov_b32_e32 v15, v2
	v_mov_b32_e32 v16, v2
	v_mov_b32_e32 v17, v2
	v_mov_b32_e32 v22, v2
	v_mov_b32_e32 v23, v2
	v_mov_b32_e32 v24, v2
	v_mov_b32_e32 v25, v2
	v_mov_b32_e32 v30, v2
	v_mov_b32_e32 v31, v2
	v_mov_b32_e32 v32, v2
	v_mov_b32_e32 v33, v2
	v_mov_b32_e32 v38, v2
	v_mov_b32_e32 v39, v2
	v_mov_b32_e32 v40, v2
	v_mov_b32_e32 v41, v2
	v_mov_b32_e32 v46, v2
	v_mov_b32_e32 v47, v2
	v_mov_b32_e32 v48, v2
	v_mov_b32_e32 v49, v2
	v_mov_b32_e32 v54, v2
	v_mov_b32_e32 v55, v2
	v_mov_b32_e32 v56, v2
	v_mov_b32_e32 v57, v2
	v_mov_b32_e32 v62, v2
	v_mov_b32_e32 v63, v2
	v_mov_b32_e32 v64, v2
	v_mov_b32_e32 v65, v2
	v_mov_b32_e32 v66, v2
	v_mov_b32_e32 v67, v2
	v_mov_b32_e32 v68, v2
	v_mov_b32_e32 v69, v2
	v_mov_b32_e32 v74, v2
	v_mov_b32_e32 v75, v2
	v_mov_b32_e32 v76, v2
	v_mov_b32_e32 v77, v2
	v_mov_b32_e32 v82, v2
	v_mov_b32_e32 v83, v2
	v_mov_b32_e32 v84, v2
	v_mov_b32_e32 v85, v2
	v_mov_b32_e32 v90, v2
	v_mov_b32_e32 v91, v2
	v_mov_b32_e32 v92, v2
	v_mov_b32_e32 v93, v2
	v_mov_b32_e32 v98, v2
	v_mov_b32_e32 v99, v2
	v_mov_b32_e32 v100, v2
	v_mov_b32_e32 v101, v2
	v_mov_b32_e32 v106, v2
	v_mov_b32_e32 v107, v2
	v_mov_b32_e32 v108, v2
	v_mov_b32_e32 v109, v2
	v_mov_b32_e32 v114, v2
	v_mov_b32_e32 v115, v2
	v_mov_b32_e32 v116, v2
	v_mov_b32_e32 v117, v2
	v_mov_b32_e32 v122, v2
	v_mov_b32_e32 v123, v2
	v_mov_b32_e32 v124, v2
	v_mov_b32_e32 v125, v2
	v_mov_b32_e32 v70, v2
	v_mov_b32_e32 v71, v2
	v_mov_b32_e32 v72, v2
	v_mov_b32_e32 v73, v2
	v_mov_b32_e32 v78, v2
	v_mov_b32_e32 v79, v2
	v_mov_b32_e32 v80, v2
	v_mov_b32_e32 v81, v2
	v_mov_b32_e32 v86, v2
	v_mov_b32_e32 v87, v2
	v_mov_b32_e32 v88, v2
	v_mov_b32_e32 v89, v2
	v_mov_b32_e32 v94, v2
	v_mov_b32_e32 v95, v2
	v_mov_b32_e32 v96, v2
	v_mov_b32_e32 v97, v2
	v_mov_b32_e32 v102, v2
	v_mov_b32_e32 v103, v2
	v_mov_b32_e32 v104, v2
	v_mov_b32_e32 v105, v2
	v_mov_b32_e32 v110, v2
	v_mov_b32_e32 v111, v2
	v_mov_b32_e32 v112, v2
	v_mov_b32_e32 v113, v2
	v_mov_b32_e32 v118, v2
	v_mov_b32_e32 v119, v2
	v_mov_b32_e32 v120, v2
	v_mov_b32_e32 v121, v2
	v_mov_b32_e32 v126, v2
	v_mov_b32_e32 v127, v2
	v_mov_b32_e32 v128, v2
	v_mov_b32_e32 v129, v2
	s_cmp_eq_u32 s93, 1
	s_cbranch_scc0 .LBB0_104
	s_add_i32 s62, s34, 2
	s_add_u32 s35, s28, 0xfffc0080
	s_addc_u32 s40, s29, -1
	s_add_i32 s63, 0, 0x10000
	s_cmp_eq_u32 s59, s34
	s_cselect_b32 s41, s21, s40
	s_cselect_b32 s40, s20, s35
	v_add_u32_e32 v145, s63, v143
	s_cselect_b32 s35, s27, s61
	s_cselect_b32 s34, s26, s60
	s_add_i32 s66, 0, 0x14000
	ds_read_b128 v[146:149], v145
	ds_read_b128 v[150:153], v145 offset:1024
	ds_read_b128 v[154:157], v145 offset:2048
	ds_read_b128 v[158:161], v145 offset:3072
	v_add_u32_e32 v145, s66, v143
	ds_read_b128 v[162:165], v145
	ds_read_b128 v[166:169], v145 offset:1024
	ds_read_b128 v[170:173], v145 offset:2048
	ds_read_b128 v[174:177], v145 offset:3072
	v_lshl_add_u64 v[218:219], s[28:29], 0, v[138:139]
	s_add_i32 m0, s45, 0xc000
	ds_read_b128 v[178:181], v144
	ds_read_b128 v[182:185], v144 offset:1024
	ds_read_b128 v[186:189], v144 offset:2048
	ds_read_b128 v[192:195], v144 offset:3072
	ds_read_b128 v[196:199], v144 offset:4096
	ds_read_b128 v[200:203], v144 offset:5120
	ds_read_b128 v[230:233], v144 offset:6144
	ds_read_b128 v[234:237], v144 offset:7168
	v_lshl_add_u64 v[218:219], s[28:29], 0, v[140:141]
	s_add_i32 m0, s45, 0xe000
	s_nop 0
	s_waitcnt vmcnt(16)
	s_waitcnt lgkmcnt(0)
	s_barrier
	s_setprio 1
	s_waitcnt lgkmcnt(0)
	v_mfma_f32_16x16x32_f16 v[126:129], v[146:149], v[178:181], v[126:129]
	v_mfma_f32_16x16x32_f16 v[118:121], v[154:157], v[178:181], v[118:121]
	v_mfma_f32_16x16x32_f16 v[110:113], v[146:149], v[186:189], v[110:113]
	v_mfma_f32_16x16x32_f16 v[102:105], v[154:157], v[186:189], v[102:105]
	v_mfma_f32_16x16x32_f16 v[94:97], v[146:149], v[196:199], v[94:97]
	v_mfma_f32_16x16x32_f16 v[86:89], v[154:157], v[196:199], v[86:89]
	v_mfma_f32_16x16x32_f16 v[78:81], v[146:149], v[230:233], v[78:81]
	v_mfma_f32_16x16x32_f16 v[70:73], v[154:157], v[230:233], v[70:73]
	v_mfma_f32_16x16x32_f16 v[126:129], v[150:153], v[182:185], v[126:129]
	v_mfma_f32_16x16x32_f16 v[118:121], v[158:161], v[182:185], v[118:121]
	v_mfma_f32_16x16x32_f16 v[110:113], v[150:153], v[192:195], v[110:113]
	v_mfma_f32_16x16x32_f16 v[102:105], v[158:161], v[192:195], v[102:105]
	v_mfma_f32_16x16x32_f16 v[94:97], v[150:153], v[200:203], v[94:97]
	v_mfma_f32_16x16x32_f16 v[86:89], v[158:161], v[200:203], v[86:89]
	v_mfma_f32_16x16x32_f16 v[78:81], v[150:153], v[234:237], v[78:81]
	v_mfma_f32_16x16x32_f16 v[70:73], v[158:161], v[234:237], v[70:73]
	s_setprio 0
	s_setprio 1
	v_mfma_f32_16x16x32_f16 v[122:125], v[162:165], v[178:181], v[122:125]
	v_mfma_f32_16x16x32_f16 v[114:117], v[170:173], v[178:181], v[114:117]
	v_mfma_f32_16x16x32_f16 v[106:109], v[162:165], v[186:189], v[106:109]
	v_mfma_f32_16x16x32_f16 v[98:101], v[170:173], v[186:189], v[98:101]
	v_mfma_f32_16x16x32_f16 v[90:93], v[162:165], v[196:199], v[90:93]
	v_mfma_f32_16x16x32_f16 v[82:85], v[170:173], v[196:199], v[82:85]
	v_mfma_f32_16x16x32_f16 v[74:77], v[162:165], v[230:233], v[74:77]
	v_mfma_f32_16x16x32_f16 v[66:69], v[170:173], v[230:233], v[66:69]
	v_mfma_f32_16x16x32_f16 v[122:125], v[166:169], v[182:185], v[122:125]
	v_mfma_f32_16x16x32_f16 v[114:117], v[174:177], v[182:185], v[114:117]
	v_mfma_f32_16x16x32_f16 v[106:109], v[166:169], v[192:195], v[106:109]
	v_mfma_f32_16x16x32_f16 v[98:101], v[174:177], v[192:195], v[98:101]
	v_mfma_f32_16x16x32_f16 v[90:93], v[166:169], v[200:203], v[90:93]
	v_mfma_f32_16x16x32_f16 v[82:85], v[174:177], v[200:203], v[82:85]
	v_mfma_f32_16x16x32_f16 v[74:77], v[166:169], v[234:237], v[74:77]
	v_mfma_f32_16x16x32_f16 v[66:69], v[174:177], v[234:237], v[66:69]
	s_setprio 0
	s_barrier
; #define PG8_STAGE(bufoff, gbase, voff) do { _Pragma("unroll") for (int _i = 0; _i < 2; ++_i) \
;         __builtin_amdgcn_global_load_lds((const unsigned*)((const char*)(gbase) + (voff)[_i]), (PG8_LAS unsigned*)(lds + (bufoff) + ldsw + _i * 8192), 16, 0, 0); } while (0)
; #define PG8_LDA(dst, b, h) do { _Pragma("unroll") for (int m = 0; m < 4; ++m) _Pragma("unroll") for (int k = 0; k < 2; ++k) dst[m][k] = *(const PG8_LAS bf16x8*)(lds + PG8_SA(b, h) + aoff + m * 2048 + k * 1024); } while (0)
; #define PG8_LDB(dst, b, h) do { _Pragma("unroll") for (int n = 0; n < 2; ++n) _Pragma("unroll") for (int k = 0; k < 2; ++k) dst[n][k] = *(const PG8_LAS bf16x8*)(lds + PG8_SB(b, h) + boff + n * 2048 + k * 1024); } while (0)
; #define PG8_WAIT_V(n) asm volatile("s_waitcnt vmcnt(" #n ")" ::: "memory")
; #define PG8_WAIT_L(n) asm volatile("s_waitcnt lgkmcnt(" #n ")" ::: "memory")
; #define PG8_BAR __builtin_amdgcn_s_barrier()
; #define PG8_SCHED __builtin_amdgcn_sched_barrier(0)
; template <class Epi, class Sched, bool ALIGN_EPI = false, bool SP2 = false>
; __device__ __forceinline__ void gemm_phase(PG8_LAS unsigned char* lds, const Gemm g, const Sched& S, const Epi& E, const int tid_in) {
;     ...
;             PG8_LDA(At, 0, 1); PG8_STAGE(PG8_SB(0, 0), b2, voffB); PG8_STAGE(PG8_SB(0, 1), b2 + hstep, voffB); PG8_STAGE(PG8_SA(0, 0), a2, voffA);
;             PG8_WAIT_V(8); PG8_WAIT_L(0); PG8_BAR; PG8_MMA(1, 0, At, B0); PG8_MMA(1, 1, At, B1); PG8_BAR; PG8_SCHED;
;             PG8_LDB(B0, 1, 0); PG8_LDB(B1, 1, 1); PG8_SCHED; PG8_LDA(At, 1, 0); PG8_STAGE(PG8_SA(0, 1), a2 + hstep, voffA);
;             PG8_WAIT_V(8); PG8_WAIT_L(0); PG8_BAR; PG8_MMA(0, 0, At, B0); PG8_MMA(0, 1, At, B1); PG8_BAR; PG8_SCHED;
	s_add_i32 s63, s63, s44
	v_lshl_add_u64 v[218:219], s[34:35], 0, v[132:133]
	s_mov_b32 m0, s63
	ds_read_b128 v[178:181], v144 offset:16384
	ds_read_b128 v[182:185], v144 offset:17408
	ds_read_b128 v[186:189], v144 offset:18432
	ds_read_b128 v[192:195], v144 offset:19456
	ds_read_b128 v[196:199], v144 offset:20480
	ds_read_b128 v[200:203], v144 offset:21504
	ds_read_b128 v[230:233], v144 offset:22528
	ds_read_b128 v[234:237], v144 offset:23552
	global_load_lds_dwordx4 v[218:219], off
	s_add_i32 m0, s63, 0x2000
	s_add_u32 s64, s34, 0x40000
	v_lshl_add_u64 v[220:221], s[34:35], 0, v[136:137]
	s_addc_u32 s65, s35, 0
	s_add_i32 s63, s66, s44
	global_load_lds_dwordx4 v[220:221], off
	v_lshl_add_u64 v[222:223], s[64:65], 0, v[132:133]
	s_mov_b32 m0, s63
	v_lshl_add_u64 v[224:225], s[40:41], 0, v[134:135]
	global_load_lds_dwordx4 v[222:223], off
	v_lshl_add_u64 v[222:223], s[64:65], 0, v[136:137]
	s_add_i32 m0, s63, 0x2000
	s_nop 0
	global_load_lds_dwordx4 v[222:223], off
	v_lshl_add_u64 v[222:223], s[40:41], 0, v[130:131]
	s_mov_b32 m0, s45
	s_nop 0
	global_load_lds_dwordx4 v[222:223], off
	s_mov_b32 m0, s47
	s_nop 0
	global_load_lds_dwordx4 v[224:225], off
	s_waitcnt vmcnt(16)
	s_waitcnt lgkmcnt(0)
	s_barrier
	s_setprio 1
	s_waitcnt lgkmcnt(0)
	v_mfma_f32_16x16x32_f16 v[62:65], v[146:149], v[178:181], v[62:65]
	v_mfma_f32_16x16x32_f16 v[54:57], v[154:157], v[178:181], v[54:57]
	v_mfma_f32_16x16x32_f16 v[46:49], v[146:149], v[186:189], v[46:49]
	v_mfma_f32_16x16x32_f16 v[38:41], v[154:157], v[186:189], v[38:41]
	v_mfma_f32_16x16x32_f16 v[30:33], v[146:149], v[196:199], v[30:33]
	v_mfma_f32_16x16x32_f16 v[22:25], v[154:157], v[196:199], v[22:25]
	v_mfma_f32_16x16x32_f16 v[14:17], v[146:149], v[230:233], v[14:17]
	v_mfma_f32_16x16x32_f16 v[6:9], v[154:157], v[230:233], v[6:9]
	v_mfma_f32_16x16x32_f16 v[62:65], v[150:153], v[182:185], v[62:65]
	v_mfma_f32_16x16x32_f16 v[54:57], v[158:161], v[182:185], v[54:57]
	v_mfma_f32_16x16x32_f16 v[46:49], v[150:153], v[192:195], v[46:49]
	v_mfma_f32_16x16x32_f16 v[38:41], v[158:161], v[192:195], v[38:41]
	v_mfma_f32_16x16x32_f16 v[30:33], v[150:153], v[200:203], v[30:33]
	v_mfma_f32_16x16x32_f16 v[22:25], v[158:161], v[200:203], v[22:25]
	v_mfma_f32_16x16x32_f16 v[14:17], v[150:153], v[234:237], v[14:17]
	v_mfma_f32_16x16x32_f16 v[6:9], v[158:161], v[234:237], v[6:9]
	s_setprio 0
	s_setprio 1
	v_mfma_f32_16x16x32_f16 v[58:61], v[162:165], v[178:181], v[58:61]
	v_mfma_f32_16x16x32_f16 v[50:53], v[170:173], v[178:181], v[50:53]
	v_mfma_f32_16x16x32_f16 v[42:45], v[162:165], v[186:189], v[42:45]
	v_mfma_f32_16x16x32_f16 v[34:37], v[170:173], v[186:189], v[34:37]
	v_mfma_f32_16x16x32_f16 v[26:29], v[162:165], v[196:199], v[26:29]
	v_mfma_f32_16x16x32_f16 v[18:21], v[170:173], v[196:199], v[18:21]
	v_mfma_f32_16x16x32_f16 v[10:13], v[162:165], v[230:233], v[10:13]
	v_mfma_f32_16x16x32_f16 v[2:5], v[170:173], v[230:233], v[2:5]
	v_mfma_f32_16x16x32_f16 v[58:61], v[166:169], v[182:185], v[58:61]
	v_mfma_f32_16x16x32_f16 v[50:53], v[174:177], v[182:185], v[50:53]
	v_mfma_f32_16x16x32_f16 v[42:45], v[166:169], v[192:195], v[42:45]
	v_mfma_f32_16x16x32_f16 v[34:37], v[174:177], v[192:195], v[34:37]
	v_mfma_f32_16x16x32_f16 v[26:29], v[166:169], v[200:203], v[26:29]
	v_mfma_f32_16x16x32_f16 v[18:21], v[174:177], v[200:203], v[18:21]
	v_mfma_f32_16x16x32_f16 v[10:13], v[166:169], v[234:237], v[10:13]
	v_mfma_f32_16x16x32_f16 v[2:5], v[174:177], v[234:237], v[2:5]
	s_setprio 0
	s_barrier
	s_add_i32 s63, 0, 0x18000
	v_add_u32_e32 v145, s63, v143
	s_add_i32 s64, 0, 0x1c000
	ds_read_b128 v[146:149], v145
	ds_read_b128 v[150:153], v145 offset:1024
	ds_read_b128 v[154:157], v145 offset:2048
	ds_read_b128 v[158:161], v145 offset:3072
	v_add_u32_e32 v145, s64, v143
	ds_read_b128 v[162:165], v145
	ds_read_b128 v[166:169], v145 offset:1024
	ds_read_b128 v[170:173], v145 offset:2048
	ds_read_b128 v[174:177], v145 offset:3072
	s_add_u32 s40, s40, 0x40000
	s_addc_u32 s41, s41, 0
	s_mov_b32 m0, s48
	v_lshl_add_u64 v[238:239], s[40:41], 0, v[130:131]
	ds_read_b128 v[178:181], v144 offset:32768
	ds_read_b128 v[182:185], v144 offset:33792
	ds_read_b128 v[186:189], v144 offset:34816
	ds_read_b128 v[192:195], v144 offset:35840
	ds_read_b128 v[196:199], v144 offset:36864
	ds_read_b128 v[200:203], v144 offset:37888
	ds_read_b128 v[230:233], v144 offset:38912
	ds_read_b128 v[234:237], v144 offset:39936
	global_load_lds_dwordx4 v[238:239], off
	v_lshl_add_u64 v[238:239], s[40:41], 0, v[134:135]
	s_mov_b32 m0, s49
	s_nop 0
	global_load_lds_dwordx4 v[238:239], off
	s_waitcnt vmcnt(16)
	s_waitcnt lgkmcnt(0)
	s_barrier
	s_setprio 1
	s_waitcnt lgkmcnt(0)
	v_mfma_f32_16x16x32_f16 v[126:129], v[146:149], v[178:181], v[126:129]
	v_mfma_f32_16x16x32_f16 v[118:121], v[154:157], v[178:181], v[118:121]
	v_mfma_f32_16x16x32_f16 v[110:113], v[146:149], v[186:189], v[110:113]
	v_mfma_f32_16x16x32_f16 v[102:105], v[154:157], v[186:189], v[102:105]
	v_mfma_f32_16x16x32_f16 v[94:97], v[146:149], v[196:199], v[94:97]
	v_mfma_f32_16x16x32_f16 v[86:89], v[154:157], v[196:199], v[86:89]
	v_mfma_f32_16x16x32_f16 v[78:81], v[146:149], v[230:233], v[78:81]
	v_mfma_f32_16x16x32_f16 v[70:73], v[154:157], v[230:233], v[70:73]
	v_mfma_f32_16x16x32_f16 v[126:129], v[150:153], v[182:185], v[126:129]
	v_mfma_f32_16x16x32_f16 v[118:121], v[158:161], v[182:185], v[118:121]
	v_mfma_f32_16x16x32_f16 v[110:113], v[150:153], v[192:195], v[110:113]
	v_mfma_f32_16x16x32_f16 v[102:105], v[158:161], v[192:195], v[102:105]
	v_mfma_f32_16x16x32_f16 v[94:97], v[150:153], v[200:203], v[94:97]
	v_mfma_f32_16x16x32_f16 v[86:89], v[158:161], v[200:203], v[86:89]
	v_mfma_f32_16x16x32_f16 v[78:81], v[150:153], v[234:237], v[78:81]
	v_mfma_f32_16x16x32_f16 v[70:73], v[158:161], v[234:237], v[70:73]
	s_setprio 0
	s_setprio 1
	v_mfma_f32_16x16x32_f16 v[122:125], v[162:165], v[178:181], v[122:125]
	v_mfma_f32_16x16x32_f16 v[114:117], v[170:173], v[178:181], v[114:117]
	v_mfma_f32_16x16x32_f16 v[106:109], v[162:165], v[186:189], v[106:109]
	v_mfma_f32_16x16x32_f16 v[98:101], v[170:173], v[186:189], v[98:101]
	v_mfma_f32_16x16x32_f16 v[90:93], v[162:165], v[196:199], v[90:93]
	v_mfma_f32_16x16x32_f16 v[82:85], v[170:173], v[196:199], v[82:85]
	v_mfma_f32_16x16x32_f16 v[74:77], v[162:165], v[230:233], v[74:77]
	v_mfma_f32_16x16x32_f16 v[66:69], v[170:173], v[230:233], v[66:69]
	v_mfma_f32_16x16x32_f16 v[122:125], v[166:169], v[182:185], v[122:125]
	v_mfma_f32_16x16x32_f16 v[114:117], v[174:177], v[182:185], v[114:117]
	v_mfma_f32_16x16x32_f16 v[106:109], v[166:169], v[192:195], v[106:109]
	v_mfma_f32_16x16x32_f16 v[98:101], v[174:177], v[192:195], v[98:101]
	v_mfma_f32_16x16x32_f16 v[90:93], v[166:169], v[200:203], v[90:93]
	v_mfma_f32_16x16x32_f16 v[82:85], v[174:177], v[200:203], v[82:85]
	v_mfma_f32_16x16x32_f16 v[74:77], v[166:169], v[234:237], v[74:77]
	v_mfma_f32_16x16x32_f16 v[66:69], v[174:177], v[234:237], v[66:69]
	s_setprio 0
	s_barrier
	s_branch .Lmid2_104

; #define PG8_STAGE(bufoff, gbase, voff) do { _Pragma("unroll") for (int _i = 0; _i < 2; ++_i) \
;         __builtin_amdgcn_global_load_lds((const unsigned*)((const char*)(gbase) + (voff)[_i]), (PG8_LAS unsigned*)(lds + (bufoff) + ldsw + _i * 8192), 16, 0, 0); } while (0)
; #define PG8_LDA(dst, b, h) do { _Pragma("unroll") for (int m = 0; m < 4; ++m) _Pragma("unroll") for (int k = 0; k < 2; ++k) dst[m][k] = *(const PG8_LAS bf16x8*)(lds + PG8_SA(b, h) + aoff + m * 2048 + k * 1024); } while (0)
; #define PG8_WAIT_V(n) asm volatile("s_waitcnt vmcnt(" #n ")" ::: "memory")
; #define PG8_WAIT_L(n) asm volatile("s_waitcnt lgkmcnt(" #n ")" ::: "memory")
; #define PG8_BAR __builtin_amdgcn_s_barrier()
; #define PG8_SCHED __builtin_amdgcn_sched_barrier(0)
; template <class Epi, class Sched, bool ALIGN_EPI = false, bool SP2 = false>
; __device__ __forceinline__ void gemm_phase(PG8_LAS unsigned char* lds, const Gemm g, const Sched& S, const Epi& E, const int tid_in) {
;     ...
;             PG8_LDA(At, 1, 1); PG8_STAGE(PG8_SB(1, 0), b3, voffB); PG8_STAGE(PG8_SB(1, 1), b3 + hstep, voffB); PG8_STAGE(PG8_SA(1, 0), a3, voffA);
;             PG8_WAIT_V(8); PG8_WAIT_L(0); PG8_BAR; PG8_MMA(1, 0, At, B0); PG8_MMA(1, 1, At, B1); PG8_BAR; PG8_SCHED;
.Lmid2_104:
	s_add_i32 s40, s63, s44
	v_lshl_add_u64 v[218:219], v[218:219], 0, s[24:25]
	s_mov_b32 m0, s40
	ds_read_b128 v[178:181], v144 offset:49152
	ds_read_b128 v[182:185], v144 offset:50176
	ds_read_b128 v[186:189], v144 offset:51200
	ds_read_b128 v[192:195], v144 offset:52224
	ds_read_b128 v[196:199], v144 offset:53248
	ds_read_b128 v[200:203], v144 offset:54272
	ds_read_b128 v[230:233], v144 offset:55296
	ds_read_b128 v[234:237], v144 offset:56320
	global_load_lds_dwordx4 v[218:219], off
	s_add_i32 m0, s40, 0x2000
	s_add_u32 s34, s34, 0x40080
	v_lshl_add_u64 v[218:219], v[220:221], 0, s[24:25]
	s_addc_u32 s35, s35, 0
	s_add_i32 s40, s64, s44
	global_load_lds_dwordx4 v[218:219], off
	v_lshl_add_u64 v[218:219], s[34:35], 0, v[132:133]
	s_mov_b32 m0, s40
	s_nop 0
	global_load_lds_dwordx4 v[218:219], off
	v_lshl_add_u64 v[218:219], s[34:35], 0, v[136:137]
	s_add_i32 m0, s40, 0x2000
	s_nop 0
	global_load_lds_dwordx4 v[218:219], off
	v_lshl_add_u64 v[218:219], v[222:223], 0, s[24:25]
	s_mov_b32 m0, s52
	s_nop 0
	global_load_lds_dwordx4 v[218:219], off
	v_lshl_add_u64 v[218:219], v[224:225], 0, s[24:25]
	s_mov_b32 m0, s53
	s_nop 0
	global_load_lds_dwordx4 v[218:219], off
	s_waitcnt vmcnt(8)
	s_waitcnt lgkmcnt(0)
	s_barrier
	s_setprio 1
	s_waitcnt lgkmcnt(0)
	v_mfma_f32_16x16x32_f16 v[62:65], v[146:149], v[178:181], v[62:65]
	v_mfma_f32_16x16x32_f16 v[54:57], v[154:157], v[178:181], v[54:57]
	v_mfma_f32_16x16x32_f16 v[46:49], v[146:149], v[186:189], v[46:49]
	v_mfma_f32_16x16x32_f16 v[38:41], v[154:157], v[186:189], v[38:41]
	v_mfma_f32_16x16x32_f16 v[30:33], v[146:149], v[196:199], v[30:33]
	v_mfma_f32_16x16x32_f16 v[22:25], v[154:157], v[196:199], v[22:25]
	v_mfma_f32_16x16x32_f16 v[14:17], v[146:149], v[230:233], v[14:17]
	v_mfma_f32_16x16x32_f16 v[6:9], v[154:157], v[230:233], v[6:9]
	v_mfma_f32_16x16x32_f16 v[62:65], v[150:153], v[182:185], v[62:65]
	v_mfma_f32_16x16x32_f16 v[54:57], v[158:161], v[182:185], v[54:57]
	v_mfma_f32_16x16x32_f16 v[46:49], v[150:153], v[192:195], v[46:49]
	v_mfma_f32_16x16x32_f16 v[38:41], v[158:161], v[192:195], v[38:41]
	v_mfma_f32_16x16x32_f16 v[30:33], v[150:153], v[200:203], v[30:33]
	v_mfma_f32_16x16x32_f16 v[22:25], v[158:161], v[200:203], v[22:25]
	v_mfma_f32_16x16x32_f16 v[14:17], v[150:153], v[234:237], v[14:17]
	v_mfma_f32_16x16x32_f16 v[6:9], v[158:161], v[234:237], v[6:9]
	s_setprio 0
	s_setprio 1
	v_mfma_f32_16x16x32_f16 v[58:61], v[162:165], v[178:181], v[58:61]
	v_mfma_f32_16x16x32_f16 v[50:53], v[170:173], v[178:181], v[50:53]
	v_mfma_f32_16x16x32_f16 v[42:45], v[162:165], v[186:189], v[42:45]
	v_mfma_f32_16x16x32_f16 v[34:37], v[170:173], v[186:189], v[34:37]
	v_mfma_f32_16x16x32_f16 v[26:29], v[162:165], v[196:199], v[26:29]
	v_mfma_f32_16x16x32_f16 v[18:21], v[170:173], v[196:199], v[18:21]
	v_mfma_f32_16x16x32_f16 v[10:13], v[162:165], v[230:233], v[10:13]
	v_mfma_f32_16x16x32_f16 v[2:5], v[170:173], v[230:233], v[2:5]
	v_mfma_f32_16x16x32_f16 v[58:61], v[166:169], v[182:185], v[58:61]
	v_mfma_f32_16x16x32_f16 v[50:53], v[174:177], v[182:185], v[50:53]
	v_mfma_f32_16x16x32_f16 v[42:45], v[166:169], v[192:195], v[42:45]
	v_mfma_f32_16x16x32_f16 v[34:37], v[174:177], v[192:195], v[34:37]
	v_mfma_f32_16x16x32_f16 v[26:29], v[166:169], v[200:203], v[26:29]
	v_mfma_f32_16x16x32_f16 v[18:21], v[174:177], v[200:203], v[18:21]
	v_mfma_f32_16x16x32_f16 v[10:13], v[166:169], v[234:237], v[10:13]
	v_mfma_f32_16x16x32_f16 v[2:5], v[174:177], v[234:237], v[2:5]
	s_setprio 0
	s_barrier
	s_add_u32 s28, s28, 0x100
	s_addc_u32 s29, s29, 0
	s_add_u32 s60, s60, 0x100
	s_addc_u32 s61, s61, 0
	s_cmp_ge_i32 s62, s16
	s_mov_b32 s34, s62
	s_cbranch_scc0 .LBB0_104
	s_mov_b64 s[60:61], 0x800
	v_readlane_b32 s62, v254, 52
	v_readlane_b32 s63, v254, 53
	s_and_b64 vcc, exec, s[14:15]
	s_cbranch_vccz .LBB0_107

; __device__ __forceinline__ float sigmoidf_(float x) { return __builtin_amdgcn_rcpf(1.f + __expf(-x)); }
;     __device__ __forceinline__ void operator()(const pg8::f32x4 (&acc)[2][2][4][2], const pg8::Unit& uu, int wr, int wc, int fr, int fq) const {
;         asm volatile("" : "+v"(fr), "+v"(fq));
;         const int upm = uu.pm & 0xffff, upn = uu.pn & 0xffff, unt = uu.pm >> 16; (void)unt;
;         const int row0 = upm * 256 + wr * 64 + fr, col = upn * 128 + wc * 32 + 8 * fq;
; #pragma unroll
;         for (int ai = 0; ai < 2; ++ai)
; #pragma unroll
;             for (int m = 0; m < 4; ++m) { float o[8];
; #pragma unroll
;                 for (int n = 0; n < 2; ++n)
; #pragma unroll
;                     for (int e = 0; e < 4; ++e) { const float g = acc[ai][0][m][n][e], up = acc[ai][1][m][n][e]; o[4 * n + e] = g * sigmoidf_(g) * up; }
;                 u32x4 w; w.x = pg8::cvt_pk_bf16(o[0], o[1]); w.y = pg8::cvt_pk_bf16(o[2], o[3]); w.z = pg8::cvt_pk_bf16(o[4], o[5]); w.w = pg8::cvt_pk_bf16(o[6], o[7]);
;                 *(u32x4*)(O + (size_t)(row0 + ai * 128 + m * 16) * DFF + col) = w; }
;     }
.LBB0_107:
	s_add_u32 s94, s20, 0x40080
	s_addc_u32 s95, s21, 0
	v_lshl_add_u64 v[248:249], s[94:95], 0, v[138:139]
	s_add_i32 m0, s45, 0xc000
	s_nop 0
	global_load_lds_dwordx4 v[248:249], off
	v_lshl_add_u64 v[248:249], s[94:95], 0, v[140:141]
	s_add_i32 m0, s45, 0xe000
	s_nop 0
	global_load_lds_dwordx4 v[248:249], off
	v_mul_f32_e32 v147, 0xbfb8aa3b, v126
	v_exp_f32_e32 v148, v147
	v_mul_f32_e32 v147, 0xbfb8aa3b, v127
	v_exp_f32_e32 v149, v147
	v_mul_f32_e32 v150, 0xbfb8aa3b, v128
	v_mul_f32_e32 v151, 0xbfb8aa3b, v129
	v_mul_f32_e32 v152, 0xbfb8aa3b, v118
	v_mul_f32_e32 v153, 0xbfb8aa3b, v119
	v_exp_f32_e32 v150, v150
	v_exp_f32_e32 v151, v151
	v_exp_f32_e32 v152, v152
	v_exp_f32_e32 v153, v153
	v_mul_f32_e32 v154, 0xbfb8aa3b, v120
	v_mul_f32_e32 v155, 0xbfb8aa3b, v121
	v_exp_f32_e32 v154, v154
	v_exp_f32_e32 v155, v155
	v_add_f32_e32 v148, 1.0, v148
	v_add_f32_e32 v149, 1.0, v149
	v_rcp_f32_e32 v148, v148
	v_rcp_f32_e32 v149, v149
	v_add_f32_e32 v150, 1.0, v150
	v_add_f32_e32 v151, 1.0, v151
	v_add_f32_e32 v152, 1.0, v152
	v_add_f32_e32 v153, 1.0, v153
	v_rcp_f32_e32 v150, v150
	v_rcp_f32_e32 v151, v151
	v_rcp_f32_e32 v152, v152
	v_rcp_f32_e32 v153, v153
	v_add_f32_e32 v154, 1.0, v154
	v_add_f32_e32 v155, 1.0, v155
	v_rcp_f32_e32 v154, v154
	v_rcp_f32_e32 v155, v155
	v_pk_mul_f32 v[126:127], v[126:127], v[148:149]
	s_lshl_b32 s28, s57, 7
	v_pk_mul_f32 v[122:123], v[122:123], v[126:127]
	v_pk_mul_f32 v[126:127], v[128:129], v[150:151]
	v_pk_mul_f32 v[118:119], v[118:119], v[152:153]
	v_mov_b32_e32 v145, v1
	v_mov_b32_e32 v146, v142
	s_lshl_b32 s16, s58, 8
	s_and_b32 s28, s28, 0x7fff80
	v_pk_mul_f32 v[124:125], v[124:125], v[126:127]
	v_pk_mul_f32 v[114:115], v[114:115], v[118:119]
	s_and_b32 s16, s16, 0xffff00
	s_or_b32 s28, s28, s51
	v_cvt_pk_f16_f32 v122, v122, v123
	v_cvt_pk_f16_f32 v123, v124, v125
	v_cvt_pk_f16_f32 v124, v114, v115
	v_pk_mul_f32 v[114:115], v[120:121], v[154:155]
	v_mul_f32_e32 v120, 0xbfb8aa3b, v110
	v_mul_f32_e32 v121, 0xbfb8aa3b, v111
	v_lshl_add_u32 v146, v146, 3, s28
	s_add_i32 s16, s16, s50
	v_pk_mul_f32 v[114:115], v[116:117], v[114:115]
	v_exp_f32_e32 v120, v120
	v_exp_f32_e32 v121, v121
	v_add_u32_e32 v145, s16, v145
	v_ashrrev_i32_e32 v147, 31, v146
	v_cvt_pk_f16_f32 v125, v114, v115
	v_mov_b64_e32 v[114:115], s[2:3]
	v_mad_i64_i32 v[118:119], s[28:29], v145, s81, v[114:115]
	v_lshlrev_b64 v[116:117], 1, v[146:147]
	v_lshl_add_u64 v[118:119], v[118:119], 0, v[116:117]
	global_store_dwordx4 v[118:119], v[122:125], off
	v_add_f32_e32 v118, 1.0, v120
	v_add_f32_e32 v119, 1.0, v121
	v_mul_f32_e32 v120, 0xbfb8aa3b, v112
	v_mul_f32_e32 v121, 0xbfb8aa3b, v113
	v_mul_f32_e32 v122, 0xbfb8aa3b, v102
	v_mul_f32_e32 v123, 0xbfb8aa3b, v103
	v_exp_f32_e32 v120, v120
	v_exp_f32_e32 v121, v121
	v_exp_f32_e32 v122, v122
	v_exp_f32_e32 v123, v123
	v_mul_f32_e32 v124, 0xbfb8aa3b, v104
	v_mul_f32_e32 v125, 0xbfb8aa3b, v105
	v_exp_f32_e32 v124, v124
	v_exp_f32_e32 v125, v125
	v_rcp_f32_e32 v118, v118
	v_rcp_f32_e32 v119, v119
	v_add_f32_e32 v120, 1.0, v120
	v_add_f32_e32 v121, 1.0, v121
	v_add_f32_e32 v122, 1.0, v122
	v_add_f32_e32 v123, 1.0, v123
	v_rcp_f32_e32 v120, v120
	v_rcp_f32_e32 v121, v121
	v_rcp_f32_e32 v122, v122
	v_rcp_f32_e32 v123, v123
	v_add_f32_e32 v124, 1.0, v124
	v_add_f32_e32 v125, 1.0, v125
	v_rcp_f32_e32 v124, v124
	v_rcp_f32_e32 v125, v125
	v_pk_mul_f32 v[110:111], v[110:111], v[118:119]
	v_pk_mul_f32 v[102:103], v[102:103], v[122:123]
	v_pk_mul_f32 v[106:107], v[106:107], v[110:111]
	v_pk_mul_f32 v[110:111], v[112:113], v[120:121]
	v_pk_mul_f32 v[98:99], v[98:99], v[102:103]
	v_pk_mul_f32 v[108:109], v[108:109], v[110:111]
	v_cvt_pk_f16_f32 v106, v106, v107
	v_cvt_pk_f16_f32 v107, v108, v109
	v_cvt_pk_f16_f32 v108, v98, v99
	v_pk_mul_f32 v[98:99], v[104:105], v[124:125]
	v_mul_f32_e32 v102, 0xbfb8aa3b, v86
	v_pk_mul_f32 v[98:99], v[100:101], v[98:99]
	v_mul_f32_e32 v100, 0xbfb8aa3b, v94
	v_mul_f32_e32 v101, 0xbfb8aa3b, v95
	v_exp_f32_e32 v100, v100
	v_exp_f32_e32 v101, v101
	v_cvt_pk_f16_f32 v109, v98, v99
	v_add_u32_e32 v98, 16, v145
	v_mad_i64_i32 v[98:99], s[28:29], v98, s81, v[114:115]
	v_lshl_add_u64 v[98:99], v[98:99], 0, v[116:117]
	global_store_dwordx4 v[98:99], v[106:109], off
	v_add_f32_e32 v98, 1.0, v100
	v_add_f32_e32 v99, 1.0, v101
	v_mul_f32_e32 v100, 0xbfb8aa3b, v96
	v_mul_f32_e32 v101, 0xbfb8aa3b, v97
	v_mul_f32_e32 v103, 0xbfb8aa3b, v87
	v_exp_f32_e32 v100, v100
	v_exp_f32_e32 v101, v101
	v_exp_f32_e32 v102, v102
	v_exp_f32_e32 v103, v103
	v_mul_f32_e32 v104, 0xbfb8aa3b, v88
	v_mul_f32_e32 v105, 0xbfb8aa3b, v89
	v_exp_f32_e32 v104, v104
	v_exp_f32_e32 v105, v105
	v_rcp_f32_e32 v98, v98
	v_rcp_f32_e32 v99, v99
	v_add_f32_e32 v100, 1.0, v100
	v_add_f32_e32 v101, 1.0, v101
	v_add_f32_e32 v102, 1.0, v102
	v_add_f32_e32 v103, 1.0, v103
	v_rcp_f32_e32 v100, v100
	v_rcp_f32_e32 v101, v101
	v_rcp_f32_e32 v102, v102
	v_rcp_f32_e32 v103, v103
	v_add_f32_e32 v104, 1.0, v104
	v_add_f32_e32 v105, 1.0, v105
	v_rcp_f32_e32 v104, v104
	v_rcp_f32_e32 v105, v105
	v_pk_mul_f32 v[94:95], v[94:95], v[98:99]
	v_pk_mul_f32 v[86:87], v[86:87], v[102:103]
	v_pk_mul_f32 v[90:91], v[90:91], v[94:95]
	v_pk_mul_f32 v[94:95], v[96:97], v[100:101]
	v_pk_mul_f32 v[82:83], v[82:83], v[86:87]
	v_pk_mul_f32 v[92:93], v[92:93], v[94:95]
	v_cvt_pk_f16_f32 v90, v90, v91
	v_cvt_pk_f16_f32 v91, v92, v93
	v_cvt_pk_f16_f32 v92, v82, v83
	v_pk_mul_f32 v[82:83], v[88:89], v[104:105]
	v_mul_f32_e32 v86, 0xbfb8aa3b, v70
	v_pk_mul_f32 v[82:83], v[84:85], v[82:83]
	v_mul_f32_e32 v84, 0xbfb8aa3b, v78
	v_mul_f32_e32 v85, 0xbfb8aa3b, v79
	v_exp_f32_e32 v84, v84
	v_exp_f32_e32 v85, v85
	v_cvt_pk_f16_f32 v93, v82, v83
	v_add_u32_e32 v82, 32, v145
; __device__ __forceinline__ float sigmoidf_(float x) { return __builtin_amdgcn_rcpf(1.f + __expf(-x)); }
;     __device__ __forceinline__ void operator()(const pg8::f32x4 (&acc)[2][2][4][2], const pg8::Unit& uu, int wr, int wc, int fr, int fq) const {
;     ...
;             for (int m = 0; m < 4; ++m) { float o[8];
; #pragma unroll
;                 for (int n = 0; n < 2; ++n)
; #pragma unroll
;                     for (int e = 0; e < 4; ++e) { const float g = acc[ai][0][m][n][e], up = acc[ai][1][m][n][e]; o[4 * n + e] = g * sigmoidf_(g) * up; }
;                 u32x4 w; w.x = pg8::cvt_pk_bf16(o[0], o[1]); w.y = pg8::cvt_pk_bf16(o[2], o[3]); w.z = pg8::cvt_pk_bf16(o[4], o[5]); w.w = pg8::cvt_pk_bf16(o[6], o[7]);
;                 *(u32x4*)(O + (size_t)(row0 + ai * 128 + m * 16) * DFF + col) = w; }
	v_mad_i64_i32 v[82:83], s[28:29], v82, s81, v[114:115]
	v_lshl_add_u64 v[82:83], v[82:83], 0, v[116:117]
	global_store_dwordx4 v[82:83], v[90:93], off
	v_add_f32_e32 v82, 1.0, v84
	v_add_f32_e32 v83, 1.0, v85
	v_mul_f32_e32 v84, 0xbfb8aa3b, v80
	v_mul_f32_e32 v85, 0xbfb8aa3b, v81
	v_mul_f32_e32 v87, 0xbfb8aa3b, v71
	v_exp_f32_e32 v84, v84
	v_exp_f32_e32 v85, v85
	v_exp_f32_e32 v86, v86
	v_exp_f32_e32 v87, v87
	v_mul_f32_e32 v88, 0xbfb8aa3b, v72
	v_mul_f32_e32 v89, 0xbfb8aa3b, v73
	v_exp_f32_e32 v88, v88
	v_exp_f32_e32 v89, v89
	v_rcp_f32_e32 v82, v82
	v_rcp_f32_e32 v83, v83
	v_add_f32_e32 v84, 1.0, v84
	v_add_f32_e32 v85, 1.0, v85
	v_add_f32_e32 v86, 1.0, v86
	v_add_f32_e32 v87, 1.0, v87
	v_rcp_f32_e32 v84, v84
	v_rcp_f32_e32 v85, v85
	v_rcp_f32_e32 v86, v86
	v_rcp_f32_e32 v87, v87
	v_add_f32_e32 v88, 1.0, v88
	v_add_f32_e32 v89, 1.0, v89
	v_rcp_f32_e32 v88, v88
	v_rcp_f32_e32 v89, v89
	v_pk_mul_f32 v[78:79], v[78:79], v[82:83]
	v_pk_mul_f32 v[70:71], v[70:71], v[86:87]
	v_pk_mul_f32 v[74:75], v[74:75], v[78:79]
	v_pk_mul_f32 v[78:79], v[80:81], v[84:85]
	v_pk_mul_f32 v[66:67], v[66:67], v[70:71]
	v_pk_mul_f32 v[76:77], v[76:77], v[78:79]
	v_cvt_pk_f16_f32 v74, v74, v75
	v_cvt_pk_f16_f32 v75, v76, v77
	v_cvt_pk_f16_f32 v76, v66, v67
	v_pk_mul_f32 v[66:67], v[72:73], v[88:89]
	v_mul_f32_e32 v70, 0xbfb8aa3b, v54
	v_pk_mul_f32 v[66:67], v[68:69], v[66:67]
	v_mul_f32_e32 v68, 0xbfb8aa3b, v64
	v_cvt_pk_f16_f32 v77, v66, v67
	v_add_u32_e32 v66, 48, v145
	v_mad_i64_i32 v[66:67], s[28:29], v66, s81, v[114:115]
	v_lshl_add_u64 v[66:67], v[66:67], 0, v[116:117]
	global_store_dwordx4 v[66:67], v[74:77], off
	v_mul_f32_e32 v66, 0xbfb8aa3b, v62
	v_mul_f32_e32 v67, 0xbfb8aa3b, v63
	v_exp_f32_e32 v66, v66
	v_exp_f32_e32 v67, v67
	v_mul_f32_e32 v69, 0xbfb8aa3b, v65
	v_mul_f32_e32 v71, 0xbfb8aa3b, v55
	v_exp_f32_e32 v68, v68
	v_exp_f32_e32 v69, v69
	v_exp_f32_e32 v70, v70
	v_exp_f32_e32 v71, v71
	v_mul_f32_e32 v72, 0xbfb8aa3b, v56
	v_mul_f32_e32 v73, 0xbfb8aa3b, v57
	v_exp_f32_e32 v72, v72
	v_exp_f32_e32 v73, v73
	v_add_f32_e32 v66, 1.0, v66
	v_add_f32_e32 v67, 1.0, v67
	v_rcp_f32_e32 v66, v66
	v_rcp_f32_e32 v67, v67
	v_add_f32_e32 v68, 1.0, v68
	v_add_f32_e32 v69, 1.0, v69
	v_add_f32_e32 v70, 1.0, v70
	v_add_f32_e32 v71, 1.0, v71
	v_rcp_f32_e32 v68, v68
	v_rcp_f32_e32 v69, v69
	v_rcp_f32_e32 v70, v70
	v_rcp_f32_e32 v71, v71
	v_add_f32_e32 v72, 1.0, v72
	v_add_f32_e32 v73, 1.0, v73
	v_rcp_f32_e32 v72, v72
	v_rcp_f32_e32 v73, v73
	v_pk_mul_f32 v[62:63], v[62:63], v[66:67]
	v_pk_mul_f32 v[54:55], v[54:55], v[70:71]
	v_pk_mul_f32 v[58:59], v[58:59], v[62:63]
	v_pk_mul_f32 v[62:63], v[64:65], v[68:69]
	v_pk_mul_f32 v[50:51], v[50:51], v[54:55]
	v_pk_mul_f32 v[60:61], v[60:61], v[62:63]
	v_cvt_pk_f16_f32 v58, v58, v59
	v_cvt_pk_f16_f32 v59, v60, v61
	v_cvt_pk_f16_f32 v60, v50, v51
	v_pk_mul_f32 v[50:51], v[56:57], v[72:73]
	v_add_u32_e32 v74, 0x80, v145
	v_pk_mul_f32 v[50:51], v[52:53], v[50:51]
	v_mul_f32_e32 v52, 0xbfb8aa3b, v46
	v_mul_f32_e32 v53, 0xbfb8aa3b, v47
	v_exp_f32_e32 v52, v52
	v_exp_f32_e32 v53, v53
	v_cvt_pk_f16_f32 v61, v50, v51
	v_mad_i64_i32 v[50:51], s[28:29], v74, s81, v[114:115]
	v_lshl_add_u64 v[50:51], v[50:51], 0, v[116:117]
	global_store_dwordx4 v[50:51], v[58:61], off
	v_add_f32_e32 v50, 1.0, v52
	v_add_f32_e32 v51, 1.0, v53
	v_mul_f32_e32 v52, 0xbfb8aa3b, v48
	v_mul_f32_e32 v53, 0xbfb8aa3b, v49
	v_mul_f32_e32 v54, 0xbfb8aa3b, v38
	v_mul_f32_e32 v55, 0xbfb8aa3b, v39
	v_exp_f32_e32 v52, v52
	v_exp_f32_e32 v53, v53
	v_exp_f32_e32 v54, v54
	v_exp_f32_e32 v55, v55
	v_mul_f32_e32 v56, 0xbfb8aa3b, v40
	v_mul_f32_e32 v57, 0xbfb8aa3b, v41
	v_exp_f32_e32 v56, v56
	v_exp_f32_e32 v57, v57
	v_rcp_f32_e32 v50, v50
	v_rcp_f32_e32 v51, v51
	v_add_f32_e32 v52, 1.0, v52
	v_add_f32_e32 v53, 1.0, v53
	v_add_f32_e32 v54, 1.0, v54
	v_add_f32_e32 v55, 1.0, v55
	v_rcp_f32_e32 v52, v52
	v_rcp_f32_e32 v53, v53
	v_rcp_f32_e32 v54, v54
	v_rcp_f32_e32 v55, v55
	v_add_f32_e32 v56, 1.0, v56
	v_add_f32_e32 v57, 1.0, v57
; __device__ __forceinline__ float sigmoidf_(float x) { return __builtin_amdgcn_rcpf(1.f + __expf(-x)); }
;     __device__ __forceinline__ void operator()(const pg8::f32x4 (&acc)[2][2][4][2], const pg8::Unit& uu, int wr, int wc, int fr, int fq) const {
;     ...
;             for (int m = 0; m < 4; ++m) { float o[8];
; #pragma unroll
;                 for (int n = 0; n < 2; ++n)
; #pragma unroll
;                     for (int e = 0; e < 4; ++e) { const float g = acc[ai][0][m][n][e], up = acc[ai][1][m][n][e]; o[4 * n + e] = g * sigmoidf_(g) * up; }
;                 u32x4 w; w.x = pg8::cvt_pk_bf16(o[0], o[1]); w.y = pg8::cvt_pk_bf16(o[2], o[3]); w.z = pg8::cvt_pk_bf16(o[4], o[5]); w.w = pg8::cvt_pk_bf16(o[6], o[7]);
;                 *(u32x4*)(O + (size_t)(row0 + ai * 128 + m * 16) * DFF + col) = w; }
	v_rcp_f32_e32 v56, v56
	v_rcp_f32_e32 v57, v57
	v_pk_mul_f32 v[46:47], v[46:47], v[50:51]
	v_pk_mul_f32 v[38:39], v[38:39], v[54:55]
	v_pk_mul_f32 v[42:43], v[42:43], v[46:47]
	v_pk_mul_f32 v[46:47], v[48:49], v[52:53]
	v_pk_mul_f32 v[34:35], v[34:35], v[38:39]
	v_pk_mul_f32 v[44:45], v[44:45], v[46:47]
	v_cvt_pk_f16_f32 v42, v42, v43
	v_cvt_pk_f16_f32 v43, v44, v45
	v_cvt_pk_f16_f32 v44, v34, v35
	v_pk_mul_f32 v[34:35], v[40:41], v[56:57]
	v_mul_f32_e32 v38, 0xbfb8aa3b, v22
	v_pk_mul_f32 v[34:35], v[36:37], v[34:35]
	v_mul_f32_e32 v36, 0xbfb8aa3b, v30
	v_mul_f32_e32 v37, 0xbfb8aa3b, v31
	v_exp_f32_e32 v36, v36
	v_exp_f32_e32 v37, v37
	v_cvt_pk_f16_f32 v45, v34, v35
	v_add_u32_e32 v34, 0x90, v145
	v_mad_i64_i32 v[34:35], s[28:29], v34, s81, v[114:115]
	v_lshl_add_u64 v[34:35], v[34:35], 0, v[116:117]
	global_store_dwordx4 v[34:35], v[42:45], off
	v_add_f32_e32 v34, 1.0, v36
	v_add_f32_e32 v35, 1.0, v37
	v_mul_f32_e32 v36, 0xbfb8aa3b, v32
	v_mul_f32_e32 v37, 0xbfb8aa3b, v33
	v_mul_f32_e32 v39, 0xbfb8aa3b, v23
	v_exp_f32_e32 v36, v36
	v_exp_f32_e32 v37, v37
	v_exp_f32_e32 v38, v38
	v_exp_f32_e32 v39, v39
	v_mul_f32_e32 v40, 0xbfb8aa3b, v24
	v_mul_f32_e32 v41, 0xbfb8aa3b, v25
	v_exp_f32_e32 v40, v40
	v_exp_f32_e32 v41, v41
	v_rcp_f32_e32 v34, v34
	v_rcp_f32_e32 v35, v35
	v_add_f32_e32 v36, 1.0, v36
	v_add_f32_e32 v37, 1.0, v37
	v_add_f32_e32 v38, 1.0, v38
	v_add_f32_e32 v39, 1.0, v39
	v_rcp_f32_e32 v36, v36
	v_rcp_f32_e32 v37, v37
	v_rcp_f32_e32 v38, v38
	v_rcp_f32_e32 v39, v39
	v_add_f32_e32 v40, 1.0, v40
	v_add_f32_e32 v41, 1.0, v41
	v_rcp_f32_e32 v40, v40
	v_rcp_f32_e32 v41, v41
	v_pk_mul_f32 v[30:31], v[30:31], v[34:35]
	v_pk_mul_f32 v[22:23], v[22:23], v[38:39]
	v_pk_mul_f32 v[26:27], v[26:27], v[30:31]
	v_pk_mul_f32 v[30:31], v[32:33], v[36:37]
	v_pk_mul_f32 v[18:19], v[18:19], v[22:23]
	v_pk_mul_f32 v[28:29], v[28:29], v[30:31]
	v_cvt_pk_f16_f32 v26, v26, v27
	v_cvt_pk_f16_f32 v27, v28, v29
	v_cvt_pk_f16_f32 v28, v18, v19
	v_pk_mul_f32 v[18:19], v[24:25], v[40:41]
	v_mul_f32_e32 v22, 0xbfb8aa3b, v6
	v_pk_mul_f32 v[18:19], v[20:21], v[18:19]
	v_mul_f32_e32 v20, 0xbfb8aa3b, v14
	v_mul_f32_e32 v21, 0xbfb8aa3b, v15
	v_exp_f32_e32 v20, v20
	v_exp_f32_e32 v21, v21
	v_cvt_pk_f16_f32 v29, v18, v19
	v_add_u32_e32 v18, 0xa0, v145
	v_mad_i64_i32 v[18:19], s[28:29], v18, s81, v[114:115]
	v_lshl_add_u64 v[18:19], v[18:19], 0, v[116:117]
	global_store_dwordx4 v[18:19], v[26:29], off
	v_add_f32_e32 v18, 1.0, v20
	v_add_f32_e32 v19, 1.0, v21
	v_mul_f32_e32 v20, 0xbfb8aa3b, v16
	v_mul_f32_e32 v21, 0xbfb8aa3b, v17
	v_mul_f32_e32 v23, 0xbfb8aa3b, v7
	v_exp_f32_e32 v20, v20
	v_exp_f32_e32 v21, v21
	v_exp_f32_e32 v22, v22
	v_exp_f32_e32 v23, v23
	v_mul_f32_e32 v24, 0xbfb8aa3b, v8
	v_mul_f32_e32 v25, 0xbfb8aa3b, v9
	v_exp_f32_e32 v24, v24
	v_exp_f32_e32 v25, v25
	v_rcp_f32_e32 v18, v18
	v_rcp_f32_e32 v19, v19
	v_add_f32_e32 v20, 1.0, v20
	v_add_f32_e32 v21, 1.0, v21
	v_add_f32_e32 v22, 1.0, v22
	v_add_f32_e32 v23, 1.0, v23
	v_rcp_f32_e32 v20, v20
	v_rcp_f32_e32 v21, v21
	v_rcp_f32_e32 v22, v22
	v_rcp_f32_e32 v23, v23
	v_add_f32_e32 v24, 1.0, v24
	v_add_f32_e32 v25, 1.0, v25
	v_rcp_f32_e32 v24, v24
	v_rcp_f32_e32 v25, v25
	v_pk_mul_f32 v[14:15], v[14:15], v[18:19]
	v_pk_mul_f32 v[6:7], v[6:7], v[22:23]
	v_pk_mul_f32 v[10:11], v[10:11], v[14:15]
	v_pk_mul_f32 v[14:15], v[16:17], v[20:21]
	v_pk_mul_f32 v[2:3], v[2:3], v[6:7]
	v_pk_mul_f32 v[12:13], v[12:13], v[14:15]
	v_cvt_pk_f16_f32 v10, v10, v11
	v_cvt_pk_f16_f32 v11, v12, v13
	v_cvt_pk_f16_f32 v12, v2, v3
	v_pk_mul_f32 v[2:3], v[8:9], v[24:25]
	s_and_b64 vcc, exec, s[38:39]
	v_pk_mul_f32 v[2:3], v[4:5], v[2:3]
	s_nop 0
	v_cvt_pk_f16_f32 v13, v2, v3
	v_add_u32_e32 v2, 0xb0, v145
	v_mad_i64_i32 v[2:3], s[28:29], v2, s81, v[114:115]
	v_lshl_add_u64 v[2:3], v[2:3], 0, v[116:117]
	s_mov_b64 s[28:29], -1
	global_store_dwordx4 v[2:3], v[10:13], off
	s_mov_b32 s93, 1
	s_cbranch_vccnz .LBB0_94
	s_andn2_b64 vcc, exec, s[0:1]
	s_cbranch_vccnz .LBB0_93
	s_barrier
	s_branch .LBB0_93
